# E1 + layer-1 ffn gate/up weight conversion moved out of phase 0 into the SSD phase, staggered (WGs 0-127 before the scan, 128-255 after it)
# speedup vs baseline: 1.0286x; 1.0035x over previous
; #define LAS __attribute__((address_space(3)))
; __device__ __forceinline__ void xpose_item(const float* src, int ld, bf16_t* dst, int K, int k0, LAS float* scr, int lane, const float* gk) {
;     if (src) {
; #pragma unroll 8
;         for (int i = 0; i < 32; ++i) { const int kk = 2 * i + (lane >> 5); scr[kk * 33 + (lane & 31)] = __builtin_nontemporal_load(src + (size_t)(k0 + kk) * ld + (lane & 31)); }
;     } else {
; #pragma unroll 8
;         for (int i = 0; i < 32; ++i) { const int kk = 2 * i + (lane >> 5); scr[kk * 33 + (lane & 31)] = 0.f; }
;     }
;     const int c = lane & 7;
;     f32x4 g0 = (f32x4){1.f, 1.f, 1.f, 1.f}, g1 = g0;
;     if (gk) { g0 = *(const f32x4*)(gk + k0 + 8 * c); g1 = *(const f32x4*)(gk + k0 + 8 * c + 4); }
; __global__ void __launch_bounds__(512) mega(Args a_byval) {
;     ...
;             it = xpose_all(a.in[23] + (size_t)lyr * D * DFF, a.in[24] + (size_t)lyr * D * DFF, DFF, 2048, 2 * DFF, 2 * DFF, 1, (bf16_t*)(ws + (lyr ? WS_W_GU : WS_W_GU0)), it, NGW, scr, lane, norm_ffn_g + lyr * D);
.LBB0_90:
	s_andn2_b64 vcc, exec, s[2:3]
	s_cbranch_vccnz .LBB0_147
	s_cmpk_gt_i32 s94, 0xff
	s_cbranch_scc1 .LBB0_147
	v_readlane_b32 s59, v255, 5
	s_cmpk_lg_i32 s59, 0x100
	s_cbranch_scc1 .Lsge_done
	s_cmpk_gt_i32 s94, 0x7f
	s_cbranch_scc1 .Lsge_done
	s_lshl_b32 s59, s94, 3
	s_add_i32 s59, s59, s95
	s_mul_i32 s64, s95, 0x2100
	v_and_b32_e32 v2, 31, v200
	v_lshrrev_b32_e32 v3, 5, v200
	v_lshlrev_b32_e32 v4, 2, v2
	v_mul_u32_u24_e32 v6, 0x84, v3
	v_add3_u32 v6, v6, v4, s64
	v_and_b32_e32 v7, 7, v200
	v_lshrrev_b32_e32 v8, 3, v200
	v_mul_u32_u24_e32 v9, 0x420, v7
	v_lshl_add_u32 v9, v8, 2, v9
	v_add_u32_e32 v9, s64, v9
	s_cmpk_ge_i32 s59, 0x2c00
	s_cbranch_scc1 .Lxpge_end
	s_load_dwordx2 s[60:61], s[92:93], 0xb8
	s_load_dwordx2 s[62:63], s[92:93], 0xe8
	s_load_dwordx2 s[64:65], s[92:93], 0x18
	v_mov_b32_e32 v5, 0x5800
	v_mul_u32_u24_e32 v5, v3, v5
	v_add_u32_e32 v5, v5, v4
	v_mov_b32_e32 v10, 0x1000
	v_mul_u32_u24_e32 v10, v8, v10
	v_lshl_add_u32 v12, v7, 4, v10
	v_add_u32_e32 v13, 0x8000, v12
	v_add_u32_e32 v14, 0x10000, v12
	v_add_u32_e32 v15, 0x18000, v12
	s_waitcnt lgkmcnt(0)
	s_add_u32 s62, s62, 0x3900000
	s_addc_u32 s63, s63, 0
	s_add_u32 s64, s64, 0x2000
	s_addc_u32 s65, s65, 0
	v_lshlrev_b32_e32 v16, 5, v7
	v_mov_b32_e32 v17, v0
	v_lshl_add_u64 v[16:17], s[64:65], 0, v[16:17]
	s_mul_hi_u32 s64, s59, 0xba2e8c
	s_mul_i32 s65, s64, 0x160
	s_sub_i32 s65, s59, s65
	s_mul_i32 s68, s64, 0x160000
	s_lshr_b32 s66, s65, 3
	s_lshl_b32 s66, s66, 9
	s_add_i32 s68, s68, s66
	s_and_b32 s66, s65, 3
	s_lshl_b32 s66, s66, 7
	s_add_i32 s68, s68, s66
	s_add_i32 s68, s68, 0x2c00000
	s_bitcmp1_b32 s65, 2
	s_movk_i32 s33, 0xb8
	s_cselect_b32 s33, 0xc0, s33
	s_load_dwordx2 s[66:67], s[92:93], s33
	s_waitcnt lgkmcnt(0)
	s_add_u32 s66, s66, s68
	s_addc_u32 s67, s67, 0
	s_lshl_b32 s64, s64, 8
	s_mov_b32 s65, 0
	v_lshl_add_u64 v[18:19], s[64:65], 0, v[16:17]
	global_load_dwordx4 v[52:55], v[18:19], off
	global_load_dwordx4 v[56:59], v[18:19], off offset:16
	v_mov_b32_e32 v11, v5
	global_load_dword v20, v11, s[66:67] nt
	v_add_u32_e32 v11, 0xb000, v11
	global_load_dword v21, v11, s[66:67] nt
	v_add_u32_e32 v11, 0xb000, v11
	global_load_dword v22, v11, s[66:67] nt
	v_add_u32_e32 v11, 0xb000, v11
	global_load_dword v23, v11, s[66:67] nt
	v_add_u32_e32 v11, 0xb000, v11
	global_load_dword v24, v11, s[66:67] nt
	v_add_u32_e32 v11, 0xb000, v11
	global_load_dword v25, v11, s[66:67] nt
	v_add_u32_e32 v11, 0xb000, v11
	global_load_dword v26, v11, s[66:67] nt
	v_add_u32_e32 v11, 0xb000, v11
	global_load_dword v27, v11, s[66:67] nt
	v_add_u32_e32 v11, 0xb000, v11
	global_load_dword v28, v11, s[66:67] nt
	v_add_u32_e32 v11, 0xb000, v11
	global_load_dword v29, v11, s[66:67] nt
	v_add_u32_e32 v11, 0xb000, v11
	global_load_dword v30, v11, s[66:67] nt
	v_add_u32_e32 v11, 0xb000, v11
	global_load_dword v31, v11, s[66:67] nt
	v_add_u32_e32 v11, 0xb000, v11
	global_load_dword v32, v11, s[66:67] nt
	v_add_u32_e32 v11, 0xb000, v11
	global_load_dword v33, v11, s[66:67] nt
	v_add_u32_e32 v11, 0xb000, v11
	global_load_dword v34, v11, s[66:67] nt
	v_add_u32_e32 v11, 0xb000, v11
	global_load_dword v35, v11, s[66:67] nt
	v_add_u32_e32 v11, 0xb000, v11
	global_load_dword v36, v11, s[66:67] nt
	v_add_u32_e32 v11, 0xb000, v11
	global_load_dword v37, v11, s[66:67] nt
	v_add_u32_e32 v11, 0xb000, v11
	global_load_dword v38, v11, s[66:67] nt
	v_add_u32_e32 v11, 0xb000, v11
	global_load_dword v39, v11, s[66:67] nt
	v_add_u32_e32 v11, 0xb000, v11
	global_load_dword v40, v11, s[66:67] nt
	v_add_u32_e32 v11, 0xb000, v11
	global_load_dword v41, v11, s[66:67] nt
	v_add_u32_e32 v11, 0xb000, v11
	global_load_dword v42, v11, s[66:67] nt
	v_add_u32_e32 v11, 0xb000, v11
	global_load_dword v43, v11, s[66:67] nt
	v_add_u32_e32 v11, 0xb000, v11
	global_load_dword v44, v11, s[66:67] nt
	v_add_u32_e32 v11, 0xb000, v11
	global_load_dword v45, v11, s[66:67] nt
	v_add_u32_e32 v11, 0xb000, v11
	global_load_dword v46, v11, s[66:67] nt
	v_add_u32_e32 v11, 0xb000, v11
	global_load_dword v47, v11, s[66:67] nt
	v_add_u32_e32 v11, 0xb000, v11
	global_load_dword v48, v11, s[66:67] nt
	v_add_u32_e32 v11, 0xb000, v11
	global_load_dword v49, v11, s[66:67] nt
	v_add_u32_e32 v11, 0xb000, v11
	global_load_dword v50, v11, s[66:67] nt
	v_add_u32_e32 v11, 0xb000, v11
	global_load_dword v51, v11, s[66:67] nt
; #define LAS __attribute__((address_space(3)))
; __device__ __forceinline__ void xpose_item(const float* src, int ld, bf16_t* dst, int K, int k0, LAS float* scr, int lane, const float* gk) {
;     if (src) {
; #pragma unroll 8
;         for (int i = 0; i < 32; ++i) { const int kk = 2 * i + (lane >> 5); scr[kk * 33 + (lane & 31)] = __builtin_nontemporal_load(src + (size_t)(k0 + kk) * ld + (lane & 31)); }
;     } else {
; #pragma unroll 8
;         for (int i = 0; i < 32; ++i) { const int kk = 2 * i + (lane >> 5); scr[kk * 33 + (lane & 31)] = 0.f; }
;     }
;     const int c = lane & 7;
;     f32x4 g0 = (f32x4){1.f, 1.f, 1.f, 1.f}, g1 = g0;
;     if (gk) { g0 = *(const f32x4*)(gk + k0 + 8 * c); g1 = *(const f32x4*)(gk + k0 + 8 * c + 4); }
.Lxpge_loop:
	s_add_i32 s32, s59, 0x800
	s_cmpk_lt_i32 s32, 0x2c00
	s_cbranch_scc0 .Lxpge_dumB
	s_mul_hi_u32 s64, s32, 0xba2e8c
	s_mul_i32 s65, s64, 0x160
	s_sub_i32 s65, s32, s65
	s_mul_i32 s68, s64, 0x160000
	s_lshr_b32 s66, s65, 3
	s_lshl_b32 s66, s66, 9
	s_add_i32 s68, s68, s66
	s_and_b32 s66, s65, 3
	s_lshl_b32 s66, s66, 7
	s_add_i32 s68, s68, s66
	s_add_i32 s68, s68, 0x2c00000
	s_bitcmp1_b32 s65, 2
	s_movk_i32 s33, 0xb8
	s_cselect_b32 s33, 0xc0, s33
	s_load_dwordx2 s[66:67], s[92:93], s33
	s_waitcnt lgkmcnt(0)
	s_add_u32 s66, s66, s68
	s_addc_u32 s67, s67, 0
	s_lshl_b32 s64, s64, 8
	s_mov_b32 s65, 0
	v_lshl_add_u64 v[18:19], s[64:65], 0, v[16:17]
	global_load_dwordx4 v[160:163], v[18:19], off
	global_load_dwordx4 v[164:167], v[18:19], off offset:16
	v_mov_b32_e32 v11, v5
	global_load_dword v108, v11, s[66:67] nt
	v_add_u32_e32 v11, 0xb000, v11
	global_load_dword v109, v11, s[66:67] nt
	v_add_u32_e32 v11, 0xb000, v11
	global_load_dword v110, v11, s[66:67] nt
	v_add_u32_e32 v11, 0xb000, v11
	global_load_dword v111, v11, s[66:67] nt
	v_add_u32_e32 v11, 0xb000, v11
	global_load_dword v112, v11, s[66:67] nt
	v_add_u32_e32 v11, 0xb000, v11
	global_load_dword v113, v11, s[66:67] nt
	v_add_u32_e32 v11, 0xb000, v11
	global_load_dword v114, v11, s[66:67] nt
	v_add_u32_e32 v11, 0xb000, v11
	global_load_dword v115, v11, s[66:67] nt
	v_add_u32_e32 v11, 0xb000, v11
	global_load_dword v116, v11, s[66:67] nt
	v_add_u32_e32 v11, 0xb000, v11
	global_load_dword v117, v11, s[66:67] nt
	v_add_u32_e32 v11, 0xb000, v11
	global_load_dword v118, v11, s[66:67] nt
	v_add_u32_e32 v11, 0xb000, v11
	global_load_dword v119, v11, s[66:67] nt
	v_add_u32_e32 v11, 0xb000, v11
	global_load_dword v120, v11, s[66:67] nt
	v_add_u32_e32 v11, 0xb000, v11
	global_load_dword v121, v11, s[66:67] nt
	v_add_u32_e32 v11, 0xb000, v11
	global_load_dword v122, v11, s[66:67] nt
	v_add_u32_e32 v11, 0xb000, v11
	global_load_dword v123, v11, s[66:67] nt
	v_add_u32_e32 v11, 0xb000, v11
	global_load_dword v124, v11, s[66:67] nt
	v_add_u32_e32 v11, 0xb000, v11
	global_load_dword v125, v11, s[66:67] nt
	v_add_u32_e32 v11, 0xb000, v11
	global_load_dword v126, v11, s[66:67] nt
	v_add_u32_e32 v11, 0xb000, v11
	global_load_dword v127, v11, s[66:67] nt
	v_add_u32_e32 v11, 0xb000, v11
	global_load_dword v128, v11, s[66:67] nt
	v_add_u32_e32 v11, 0xb000, v11
	global_load_dword v129, v11, s[66:67] nt
	v_add_u32_e32 v11, 0xb000, v11
	global_load_dword v130, v11, s[66:67] nt
	v_add_u32_e32 v11, 0xb000, v11
	global_load_dword v131, v11, s[66:67] nt
	v_add_u32_e32 v11, 0xb000, v11
	global_load_dword v132, v11, s[66:67] nt
	v_add_u32_e32 v11, 0xb000, v11
	global_load_dword v133, v11, s[66:67] nt
	v_add_u32_e32 v11, 0xb000, v11
	global_load_dword v134, v11, s[66:67] nt
	v_add_u32_e32 v11, 0xb000, v11
	global_load_dword v135, v11, s[66:67] nt
	v_add_u32_e32 v11, 0xb000, v11
	global_load_dword v136, v11, s[66:67] nt
	v_add_u32_e32 v11, 0xb000, v11
	global_load_dword v137, v11, s[66:67] nt
	v_add_u32_e32 v11, 0xb000, v11
	global_load_dword v138, v11, s[66:67] nt
	v_add_u32_e32 v11, 0xb000, v11
	global_load_dword v139, v11, s[66:67] nt
	s_branch .Lxpge_procA

; #define LAS __attribute__((address_space(3)))
; __device__ __forceinline__ unsigned cvt_pk_bf16(float lo, float hi) { unsigned r; asm volatile("v_cvt_pk_bf16_f32 %0, %1, %2" : "=v"(r) : "v"(lo), "v"(hi)); return r; }
; __device__ __forceinline__ void xpose_item(const float* src, int ld, bf16_t* dst, int K, int k0, LAS float* scr, int lane, const float* gk) {
;     ...
;         for (int i = 0; i < 32; ++i) { const int kk = 2 * i + (lane >> 5); scr[kk * 33 + (lane & 31)] = __builtin_nontemporal_load(src + (size_t)(k0 + kk) * ld + (lane & 31)); }
;     } else {
; #pragma unroll 8
;         for (int i = 0; i < 32; ++i) { const int kk = 2 * i + (lane >> 5); scr[kk * 33 + (lane & 31)] = 0.f; }
;     }
;     const int c = lane & 7;
;     f32x4 g0 = (f32x4){1.f, 1.f, 1.f, 1.f}, g1 = g0;
;     if (gk) { g0 = *(const f32x4*)(gk + k0 + 8 * c); g1 = *(const f32x4*)(gk + k0 + 8 * c + 4); }
;     asm volatile("s_waitcnt lgkmcnt(0)" ::: "memory");
; #pragma unroll
;     for (int j = 0; j < 4; ++j) { const int n = (lane >> 3) + 8 * j; const LAS float* s = scr + (8 * c) * 33 + n;
;         u32x4 o; o.x = cvt_pk_bf16(s[0 * 33] * g0[0], s[1 * 33] * g0[1]); o.y = cvt_pk_bf16(s[2 * 33] * g0[2], s[3 * 33] * g0[3]); o.z = cvt_pk_bf16(s[4 * 33] * g1[0], s[5 * 33] * g1[1]); o.w = cvt_pk_bf16(s[6 * 33] * g1[2], s[7 * 33] * g1[3]);
;         *(u32x4*)(dst + (size_t)n * K + k0 + 8 * c) = o; }
.Lxpge_procA:
	s_mul_hi_u32 s64, s59, 0xba2e8c
	s_mul_i32 s65, s64, 0x160
	s_sub_i32 s65, s59, s65
	s_mul_i32 s68, s65, 0x20000
	s_lshl_b32 s64, s64, 7
	s_add_i32 s68, s68, s64
	s_add_u32 s64, s62, s68
	s_addc_u32 s65, s63, 0
	s_waitcnt vmcnt(63)
	ds_write_b32 v6, v20 offset:0
	s_waitcnt vmcnt(62)
	ds_write_b32 v6, v21 offset:264
	s_waitcnt vmcnt(61)
	ds_write_b32 v6, v22 offset:528
	s_waitcnt vmcnt(60)
	ds_write_b32 v6, v23 offset:792
	s_waitcnt vmcnt(59)
	ds_write_b32 v6, v24 offset:1056
	s_waitcnt vmcnt(58)
	ds_write_b32 v6, v25 offset:1320
	s_waitcnt vmcnt(57)
	ds_write_b32 v6, v26 offset:1584
	s_waitcnt vmcnt(56)
	ds_write_b32 v6, v27 offset:1848
	s_waitcnt vmcnt(55)
	ds_write_b32 v6, v28 offset:2112
	s_waitcnt vmcnt(54)
	ds_write_b32 v6, v29 offset:2376
	s_waitcnt vmcnt(53)
	ds_write_b32 v6, v30 offset:2640
	s_waitcnt vmcnt(52)
	ds_write_b32 v6, v31 offset:2904
	s_waitcnt vmcnt(51)
	ds_write_b32 v6, v32 offset:3168
	s_waitcnt vmcnt(50)
	ds_write_b32 v6, v33 offset:3432
	s_waitcnt vmcnt(49)
	ds_write_b32 v6, v34 offset:3696
	s_waitcnt vmcnt(48)
	ds_write_b32 v6, v35 offset:3960
	s_waitcnt vmcnt(47)
	ds_write_b32 v6, v36 offset:4224
	s_waitcnt vmcnt(46)
	ds_write_b32 v6, v37 offset:4488
	s_waitcnt vmcnt(45)
	ds_write_b32 v6, v38 offset:4752
	s_waitcnt vmcnt(44)
	ds_write_b32 v6, v39 offset:5016
	s_waitcnt vmcnt(43)
	ds_write_b32 v6, v40 offset:5280
	s_waitcnt vmcnt(42)
	ds_write_b32 v6, v41 offset:5544
	s_waitcnt vmcnt(41)
	ds_write_b32 v6, v42 offset:5808
	s_waitcnt vmcnt(40)
	ds_write_b32 v6, v43 offset:6072
	s_waitcnt vmcnt(39)
	ds_write_b32 v6, v44 offset:6336
	s_waitcnt vmcnt(38)
	ds_write_b32 v6, v45 offset:6600
	s_waitcnt vmcnt(37)
	ds_write_b32 v6, v46 offset:6864
	s_waitcnt vmcnt(36)
	ds_write_b32 v6, v47 offset:7128
	s_waitcnt vmcnt(35)
	ds_write_b32 v6, v48 offset:7392
	s_waitcnt vmcnt(34)
	ds_write_b32 v6, v49 offset:7656
	s_waitcnt vmcnt(33)
	ds_write_b32 v6, v50 offset:7920
	s_waitcnt vmcnt(32)
	ds_write_b32 v6, v51 offset:8184
	s_waitcnt lgkmcnt(0)
	ds_read2_b32 v[60:61], v9 offset0:0 offset1:33
	ds_read2_b32 v[62:63], v9 offset0:66 offset1:99
	ds_read2_b32 v[64:65], v9 offset0:132 offset1:165
	ds_read2_b32 v[66:67], v9 offset0:198 offset1:231
	ds_read2_b32 v[68:69], v9 offset0:8 offset1:41
	ds_read2_b32 v[70:71], v9 offset0:74 offset1:107
	ds_read2_b32 v[72:73], v9 offset0:140 offset1:173
	ds_read2_b32 v[74:75], v9 offset0:206 offset1:239
	ds_read2_b32 v[76:77], v9 offset0:16 offset1:49
	ds_read2_b32 v[78:79], v9 offset0:82 offset1:115
	ds_read2_b32 v[80:81], v9 offset0:148 offset1:181
	ds_read2_b32 v[82:83], v9 offset0:214 offset1:247
	ds_read2_b32 v[84:85], v9 offset0:24 offset1:57
	ds_read2_b32 v[86:87], v9 offset0:90 offset1:123
	ds_read2_b32 v[88:89], v9 offset0:156 offset1:189
	ds_read2_b32 v[90:91], v9 offset0:222 offset1:255
	s_waitcnt lgkmcnt(12)
	v_mul_f32_e32 v60, v60, v52
	v_mul_f32_e32 v61, v61, v53
	v_mul_f32_e32 v62, v62, v54
	v_mul_f32_e32 v63, v63, v55
	v_mul_f32_e32 v64, v64, v56
	v_mul_f32_e32 v65, v65, v57
	v_mul_f32_e32 v66, v66, v58
	v_mul_f32_e32 v67, v67, v59
	v_cvt_pk_bf16_f32 v92, v60, v61
	v_cvt_pk_bf16_f32 v93, v62, v63
	v_cvt_pk_bf16_f32 v94, v64, v65
	v_cvt_pk_bf16_f32 v95, v66, v67
	global_store_dwordx4 v12, v[92:95], s[64:65]
	s_waitcnt lgkmcnt(8)
	v_mul_f32_e32 v68, v68, v52
	v_mul_f32_e32 v69, v69, v53
	v_mul_f32_e32 v70, v70, v54
	v_mul_f32_e32 v71, v71, v55
	v_mul_f32_e32 v72, v72, v56
	v_mul_f32_e32 v73, v73, v57
	v_mul_f32_e32 v74, v74, v58
	v_mul_f32_e32 v75, v75, v59
	v_cvt_pk_bf16_f32 v96, v68, v69
	v_cvt_pk_bf16_f32 v97, v70, v71
	v_cvt_pk_bf16_f32 v98, v72, v73
	v_cvt_pk_bf16_f32 v99, v74, v75
	global_store_dwordx4 v13, v[96:99], s[64:65]
	s_waitcnt lgkmcnt(4)
	v_mul_f32_e32 v76, v76, v52
	v_mul_f32_e32 v77, v77, v53
	v_mul_f32_e32 v78, v78, v54
	v_mul_f32_e32 v79, v79, v55
	v_mul_f32_e32 v80, v80, v56
	v_mul_f32_e32 v81, v81, v57
	v_mul_f32_e32 v82, v82, v58
	v_mul_f32_e32 v83, v83, v59
	v_cvt_pk_bf16_f32 v100, v76, v77
	v_cvt_pk_bf16_f32 v101, v78, v79
	v_cvt_pk_bf16_f32 v102, v80, v81
	v_cvt_pk_bf16_f32 v103, v82, v83
	global_store_dwordx4 v14, v[100:103], s[64:65]
	s_waitcnt lgkmcnt(0)
	v_mul_f32_e32 v84, v84, v52
	v_mul_f32_e32 v85, v85, v53
	v_mul_f32_e32 v86, v86, v54
	v_mul_f32_e32 v87, v87, v55
	v_mul_f32_e32 v88, v88, v56
	v_mul_f32_e32 v89, v89, v57
	v_mul_f32_e32 v90, v90, v58
	v_mul_f32_e32 v91, v91, v59
	v_cvt_pk_bf16_f32 v104, v84, v85
	v_cvt_pk_bf16_f32 v105, v86, v87
	v_cvt_pk_bf16_f32 v106, v88, v89
	v_cvt_pk_bf16_f32 v107, v90, v91
	global_store_dwordx4 v15, v[104:107], s[64:65]
	s_cmpk_lt_i32 s32, 0x2c00
	s_cbranch_scc0 .Lxpge_fin
; #define LAS __attribute__((address_space(3)))
; __device__ __forceinline__ void xpose_item(const float* src, int ld, bf16_t* dst, int K, int k0, LAS float* scr, int lane, const float* gk) {
;     if (src) {
; #pragma unroll 8
;         for (int i = 0; i < 32; ++i) { const int kk = 2 * i + (lane >> 5); scr[kk * 33 + (lane & 31)] = __builtin_nontemporal_load(src + (size_t)(k0 + kk) * ld + (lane & 31)); }
;     } else {
; #pragma unroll 8
;         for (int i = 0; i < 32; ++i) { const int kk = 2 * i + (lane >> 5); scr[kk * 33 + (lane & 31)] = 0.f; }
;     }
;     const int c = lane & 7;
;     f32x4 g0 = (f32x4){1.f, 1.f, 1.f, 1.f}, g1 = g0;
;     if (gk) { g0 = *(const f32x4*)(gk + k0 + 8 * c); g1 = *(const f32x4*)(gk + k0 + 8 * c + 4); }
	s_add_i32 s59, s32, 0x800
	s_cmpk_lt_i32 s59, 0x2c00
	s_cbranch_scc0 .Lxpge_dumA
	s_mul_hi_u32 s64, s59, 0xba2e8c
	s_mul_i32 s65, s64, 0x160
	s_sub_i32 s65, s59, s65
	s_mul_i32 s68, s64, 0x160000
	s_lshr_b32 s66, s65, 3
	s_lshl_b32 s66, s66, 9
	s_add_i32 s68, s68, s66
	s_and_b32 s66, s65, 3
	s_lshl_b32 s66, s66, 7
	s_add_i32 s68, s68, s66
	s_add_i32 s68, s68, 0x2c00000
	s_bitcmp1_b32 s65, 2
	s_movk_i32 s33, 0xb8
	s_cselect_b32 s33, 0xc0, s33
	s_load_dwordx2 s[66:67], s[92:93], s33
	s_waitcnt lgkmcnt(0)
	s_add_u32 s66, s66, s68
	s_addc_u32 s67, s67, 0
	s_lshl_b32 s64, s64, 8
	s_mov_b32 s65, 0
	v_lshl_add_u64 v[18:19], s[64:65], 0, v[16:17]
	global_load_dwordx4 v[52:55], v[18:19], off
	global_load_dwordx4 v[56:59], v[18:19], off offset:16
	v_mov_b32_e32 v11, v5
	global_load_dword v20, v11, s[66:67] nt
	v_add_u32_e32 v11, 0xb000, v11
	global_load_dword v21, v11, s[66:67] nt
	v_add_u32_e32 v11, 0xb000, v11
	global_load_dword v22, v11, s[66:67] nt
	v_add_u32_e32 v11, 0xb000, v11
	global_load_dword v23, v11, s[66:67] nt
	v_add_u32_e32 v11, 0xb000, v11
	global_load_dword v24, v11, s[66:67] nt
	v_add_u32_e32 v11, 0xb000, v11
	global_load_dword v25, v11, s[66:67] nt
	v_add_u32_e32 v11, 0xb000, v11
	global_load_dword v26, v11, s[66:67] nt
	v_add_u32_e32 v11, 0xb000, v11
	global_load_dword v27, v11, s[66:67] nt
	v_add_u32_e32 v11, 0xb000, v11
	global_load_dword v28, v11, s[66:67] nt
	v_add_u32_e32 v11, 0xb000, v11
	global_load_dword v29, v11, s[66:67] nt
	v_add_u32_e32 v11, 0xb000, v11
	global_load_dword v30, v11, s[66:67] nt
	v_add_u32_e32 v11, 0xb000, v11
	global_load_dword v31, v11, s[66:67] nt
	v_add_u32_e32 v11, 0xb000, v11
	global_load_dword v32, v11, s[66:67] nt
	v_add_u32_e32 v11, 0xb000, v11
	global_load_dword v33, v11, s[66:67] nt
	v_add_u32_e32 v11, 0xb000, v11
	global_load_dword v34, v11, s[66:67] nt
	v_add_u32_e32 v11, 0xb000, v11
	global_load_dword v35, v11, s[66:67] nt
	v_add_u32_e32 v11, 0xb000, v11
	global_load_dword v36, v11, s[66:67] nt
	v_add_u32_e32 v11, 0xb000, v11
	global_load_dword v37, v11, s[66:67] nt
	v_add_u32_e32 v11, 0xb000, v11
	global_load_dword v38, v11, s[66:67] nt
	v_add_u32_e32 v11, 0xb000, v11
	global_load_dword v39, v11, s[66:67] nt
	v_add_u32_e32 v11, 0xb000, v11
	global_load_dword v40, v11, s[66:67] nt
	v_add_u32_e32 v11, 0xb000, v11
	global_load_dword v41, v11, s[66:67] nt
	v_add_u32_e32 v11, 0xb000, v11
	global_load_dword v42, v11, s[66:67] nt
	v_add_u32_e32 v11, 0xb000, v11
	global_load_dword v43, v11, s[66:67] nt
	v_add_u32_e32 v11, 0xb000, v11
	global_load_dword v44, v11, s[66:67] nt
	v_add_u32_e32 v11, 0xb000, v11
	global_load_dword v45, v11, s[66:67] nt
	v_add_u32_e32 v11, 0xb000, v11
	global_load_dword v46, v11, s[66:67] nt
	v_add_u32_e32 v11, 0xb000, v11
	global_load_dword v47, v11, s[66:67] nt
	v_add_u32_e32 v11, 0xb000, v11
	global_load_dword v48, v11, s[66:67] nt
	v_add_u32_e32 v11, 0xb000, v11
	global_load_dword v49, v11, s[66:67] nt
	v_add_u32_e32 v11, 0xb000, v11
	global_load_dword v50, v11, s[66:67] nt
	v_add_u32_e32 v11, 0xb000, v11
	global_load_dword v51, v11, s[66:67] nt
	s_branch .Lxpge_procB

; #define LAS __attribute__((address_space(3)))
; __device__ __forceinline__ unsigned cvt_pk_bf16(float lo, float hi) { unsigned r; asm volatile("v_cvt_pk_bf16_f32 %0, %1, %2" : "=v"(r) : "v"(lo), "v"(hi)); return r; }
; __device__ __forceinline__ void xpose_item(const float* src, int ld, bf16_t* dst, int K, int k0, LAS float* scr, int lane, const float* gk) {
;     ...
;         for (int i = 0; i < 32; ++i) { const int kk = 2 * i + (lane >> 5); scr[kk * 33 + (lane & 31)] = __builtin_nontemporal_load(src + (size_t)(k0 + kk) * ld + (lane & 31)); }
;     } else {
; #pragma unroll 8
;         for (int i = 0; i < 32; ++i) { const int kk = 2 * i + (lane >> 5); scr[kk * 33 + (lane & 31)] = 0.f; }
;     }
;     const int c = lane & 7;
;     f32x4 g0 = (f32x4){1.f, 1.f, 1.f, 1.f}, g1 = g0;
;     if (gk) { g0 = *(const f32x4*)(gk + k0 + 8 * c); g1 = *(const f32x4*)(gk + k0 + 8 * c + 4); }
;     asm volatile("s_waitcnt lgkmcnt(0)" ::: "memory");
; #pragma unroll
;     for (int j = 0; j < 4; ++j) { const int n = (lane >> 3) + 8 * j; const LAS float* s = scr + (8 * c) * 33 + n;
;         u32x4 o; o.x = cvt_pk_bf16(s[0 * 33] * g0[0], s[1 * 33] * g0[1]); o.y = cvt_pk_bf16(s[2 * 33] * g0[2], s[3 * 33] * g0[3]); o.z = cvt_pk_bf16(s[4 * 33] * g1[0], s[5 * 33] * g1[1]); o.w = cvt_pk_bf16(s[6 * 33] * g1[2], s[7 * 33] * g1[3]);
;         *(u32x4*)(dst + (size_t)n * K + k0 + 8 * c) = o; }
.Lxpge_procB:
	s_mul_hi_u32 s64, s32, 0xba2e8c
	s_mul_i32 s65, s64, 0x160
	s_sub_i32 s65, s32, s65
	s_mul_i32 s68, s65, 0x20000
	s_lshl_b32 s64, s64, 7
	s_add_i32 s68, s68, s64
	s_add_u32 s64, s62, s68
	s_addc_u32 s65, s63, 0
	s_waitcnt vmcnt(63)
	ds_write_b32 v6, v108 offset:0
	s_waitcnt vmcnt(62)
	ds_write_b32 v6, v109 offset:264
	s_waitcnt vmcnt(61)
	ds_write_b32 v6, v110 offset:528
	s_waitcnt vmcnt(60)
	ds_write_b32 v6, v111 offset:792
	s_waitcnt vmcnt(59)
	ds_write_b32 v6, v112 offset:1056
	s_waitcnt vmcnt(58)
	ds_write_b32 v6, v113 offset:1320
	s_waitcnt vmcnt(57)
	ds_write_b32 v6, v114 offset:1584
	s_waitcnt vmcnt(56)
	ds_write_b32 v6, v115 offset:1848
	s_waitcnt vmcnt(55)
	ds_write_b32 v6, v116 offset:2112
	s_waitcnt vmcnt(54)
	ds_write_b32 v6, v117 offset:2376
	s_waitcnt vmcnt(53)
	ds_write_b32 v6, v118 offset:2640
	s_waitcnt vmcnt(52)
	ds_write_b32 v6, v119 offset:2904
	s_waitcnt vmcnt(51)
	ds_write_b32 v6, v120 offset:3168
	s_waitcnt vmcnt(50)
	ds_write_b32 v6, v121 offset:3432
	s_waitcnt vmcnt(49)
	ds_write_b32 v6, v122 offset:3696
	s_waitcnt vmcnt(48)
	ds_write_b32 v6, v123 offset:3960
	s_waitcnt vmcnt(47)
	ds_write_b32 v6, v124 offset:4224
	s_waitcnt vmcnt(46)
	ds_write_b32 v6, v125 offset:4488
	s_waitcnt vmcnt(45)
	ds_write_b32 v6, v126 offset:4752
	s_waitcnt vmcnt(44)
	ds_write_b32 v6, v127 offset:5016
	s_waitcnt vmcnt(43)
	ds_write_b32 v6, v128 offset:5280
	s_waitcnt vmcnt(42)
	ds_write_b32 v6, v129 offset:5544
	s_waitcnt vmcnt(41)
	ds_write_b32 v6, v130 offset:5808
	s_waitcnt vmcnt(40)
	ds_write_b32 v6, v131 offset:6072
	s_waitcnt vmcnt(39)
	ds_write_b32 v6, v132 offset:6336
	s_waitcnt vmcnt(38)
	ds_write_b32 v6, v133 offset:6600
	s_waitcnt vmcnt(37)
	ds_write_b32 v6, v134 offset:6864
	s_waitcnt vmcnt(36)
	ds_write_b32 v6, v135 offset:7128
	s_waitcnt vmcnt(35)
	ds_write_b32 v6, v136 offset:7392
	s_waitcnt vmcnt(34)
	ds_write_b32 v6, v137 offset:7656
	s_waitcnt vmcnt(33)
	ds_write_b32 v6, v138 offset:7920
	s_waitcnt vmcnt(32)
	ds_write_b32 v6, v139 offset:8184
	s_waitcnt lgkmcnt(0)
	ds_read2_b32 v[60:61], v9 offset0:0 offset1:33
	ds_read2_b32 v[62:63], v9 offset0:66 offset1:99
	ds_read2_b32 v[64:65], v9 offset0:132 offset1:165
	ds_read2_b32 v[66:67], v9 offset0:198 offset1:231
	ds_read2_b32 v[68:69], v9 offset0:8 offset1:41
	ds_read2_b32 v[70:71], v9 offset0:74 offset1:107
	ds_read2_b32 v[72:73], v9 offset0:140 offset1:173
	ds_read2_b32 v[74:75], v9 offset0:206 offset1:239
	ds_read2_b32 v[76:77], v9 offset0:16 offset1:49
	ds_read2_b32 v[78:79], v9 offset0:82 offset1:115
	ds_read2_b32 v[80:81], v9 offset0:148 offset1:181
	ds_read2_b32 v[82:83], v9 offset0:214 offset1:247
	ds_read2_b32 v[84:85], v9 offset0:24 offset1:57
	ds_read2_b32 v[86:87], v9 offset0:90 offset1:123
	ds_read2_b32 v[88:89], v9 offset0:156 offset1:189
	ds_read2_b32 v[90:91], v9 offset0:222 offset1:255
	s_waitcnt lgkmcnt(12)
	v_mul_f32_e32 v60, v60, v160
	v_mul_f32_e32 v61, v61, v161
	v_mul_f32_e32 v62, v62, v162
	v_mul_f32_e32 v63, v63, v163
	v_mul_f32_e32 v64, v64, v164
	v_mul_f32_e32 v65, v65, v165
	v_mul_f32_e32 v66, v66, v166
	v_mul_f32_e32 v67, v67, v167
	v_cvt_pk_bf16_f32 v92, v60, v61
	v_cvt_pk_bf16_f32 v93, v62, v63
	v_cvt_pk_bf16_f32 v94, v64, v65
	v_cvt_pk_bf16_f32 v95, v66, v67
	global_store_dwordx4 v12, v[92:95], s[64:65]
	s_waitcnt lgkmcnt(8)
	v_mul_f32_e32 v68, v68, v160
	v_mul_f32_e32 v69, v69, v161
	v_mul_f32_e32 v70, v70, v162
	v_mul_f32_e32 v71, v71, v163
	v_mul_f32_e32 v72, v72, v164
	v_mul_f32_e32 v73, v73, v165
	v_mul_f32_e32 v74, v74, v166
	v_mul_f32_e32 v75, v75, v167
	v_cvt_pk_bf16_f32 v96, v68, v69
	v_cvt_pk_bf16_f32 v97, v70, v71
	v_cvt_pk_bf16_f32 v98, v72, v73
	v_cvt_pk_bf16_f32 v99, v74, v75
	global_store_dwordx4 v13, v[96:99], s[64:65]
	s_waitcnt lgkmcnt(4)
	v_mul_f32_e32 v76, v76, v160
	v_mul_f32_e32 v77, v77, v161
	v_mul_f32_e32 v78, v78, v162
	v_mul_f32_e32 v79, v79, v163
	v_mul_f32_e32 v80, v80, v164
	v_mul_f32_e32 v81, v81, v165
	v_mul_f32_e32 v82, v82, v166
	v_mul_f32_e32 v83, v83, v167
	v_cvt_pk_bf16_f32 v100, v76, v77
	v_cvt_pk_bf16_f32 v101, v78, v79
	v_cvt_pk_bf16_f32 v102, v80, v81
	v_cvt_pk_bf16_f32 v103, v82, v83
	global_store_dwordx4 v14, v[100:103], s[64:65]
	s_waitcnt lgkmcnt(0)
	v_mul_f32_e32 v84, v84, v160
	v_mul_f32_e32 v85, v85, v161
	v_mul_f32_e32 v86, v86, v162
	v_mul_f32_e32 v87, v87, v163
	v_mul_f32_e32 v88, v88, v164
	v_mul_f32_e32 v89, v89, v165
	v_mul_f32_e32 v90, v90, v166
	v_mul_f32_e32 v91, v91, v167
	v_cvt_pk_bf16_f32 v104, v84, v85
	v_cvt_pk_bf16_f32 v105, v86, v87
	v_cvt_pk_bf16_f32 v106, v88, v89
	v_cvt_pk_bf16_f32 v107, v90, v91
	global_store_dwordx4 v15, v[104:107], s[64:65]
	s_cmpk_lt_i32 s59, 0x2c00
	s_cbranch_scc1 .Lxpge_loop
	s_branch .Lxpge_drain

; #define LAS __attribute__((address_space(3)))
; #define SSD_SCAN(buf) do { const int l0 = 2 * lane; const float a0 = A * d0, a1 = A * d1; float incl = a0 + a1; \
;             _Pragma("unroll") for (int o = 1; o < 64; o <<= 1) { const float tv = __shfl_up(incl, o); if (lane >= o) incl += tv; } \
;             (buf)[l0 + 1] = incl; (buf)[l0] = incl - a1; (buf)[128 + l0] = d0; (buf)[128 + l0 + 1] = d1; } while (0)
; __device__ __forceinline__ void ssd_phase(const bf16_t* XBC, const float* DT  , const ss_t* SSq, const float* dtb, const bf16_t* Z, const float* a_log, const float* d_skip, bf16_t* YS, LAS unsigned char* lds, int tid, int wid, int lane, int bid, int G) {
;     const int fr = lane & 15, fq = lane >> 4;
;     LAS bf16_t* Ct = (LAS bf16_t*)(lds + SS_CT); LAS bf16_t* Bt = (LAS bf16_t*)(lds + SS_BT); LAS bf16_t* XT = (LAS bf16_t*)(lds + SS_XT); LAS bf16_t* XW = (LAS bf16_t*)(lds + SS_XW);
;     LAS bf16_t* Sin = (LAS bf16_t*)(lds + SS_SIN); LAS float* csbuf = (LAS float*)(lds + SS_CS);
;     for (int w = bid; w < 256; w += G) {
;         const int b = w >> 6, h = w & 63, g = h >> 3;
;         const float A = -expf(a_log[h]), Dh = d_skip[h], dtbh = dtb[h];
;         f32x4 Sacc[4];
; #pragma unroll
;         for (int pt = 0; pt < 4; ++pt) Sacc[pt] = (f32x4){0.f, 0.f, 0.f, 0.f};
;         u32x4 cr[4], br[4], xr2[2]; float d0 = 0.f, d1 = 0.f;
;         const unsigned voffC = (unsigned)(((tid >> 4) * SSD_CONV + 5120 + g * 128 + (tid & 15) * 8) * 2), voffX = (unsigned)(((tid & 127) * SSD_CONV + h * 64 + (tid >> 7) * 8) * 2);
;     ...
;         SSD_GLOADS(0);
;         if (wid == 0) { SSD_DTLOAD(0); SSD_SCAN(csbuf); SSD_DTLOAD(1); }
.Lxpge_end:
	s_sub_i32 s59, s59, 0x2c00
	s_movk_i32 s33, 0x84
	s_waitcnt lgkmcnt(0)
	s_barrier
.Lsge_done:
	s_sub_i32 s30, 11, s95
	s_cmp_gt_i32 s95, 3
	s_cselect_b32 s95, s30, s95
	s_load_dwordx2 s[6:7], s[92:93], 0xe8
	v_writelane_b32 v255, s76, 6
	v_writelane_b32 v255, s72, 7
	v_ashrrev_i32_e32 v5, 4, v212
	s_waitcnt lgkmcnt(0)
	v_lshlrev_b32_e32 v3, 3, v212
	v_writelane_b32 v255, s73, 8
	v_writelane_b32 v255, s74, 9
	v_mul_lo_u32 v2, v5, s83
	v_and_b32_e32 v6, 0x78, v3
	v_writelane_b32 v255, s75, 10
	s_add_u32 s2, s6, 0x1ac00000
	v_or_b32_e32 v7, v2, v6
	v_lshlrev_b32_e32 v2, 4, v211
	v_mov_b32_e32 v3, v0
	v_writelane_b32 v255, s2, 11
	s_addc_u32 s2, s7, 0
	v_lshrrev_b32_e32 v4, 4, v211
	v_lshl_add_u64 v[2:3], s[6:7], 0, v[2:3]
	s_mov_b64 s[6:7], 0x20e30000
	v_add_u32_e32 v15, 0x400, v212
	v_lshl_add_u64 v[108:109], v[2:3], 0, s[6:7]
	v_lshlrev_b32_e32 v3, 3, v4
	v_lshl_add_u32 v2, v6, 1, 0
	s_movk_i32 s28, 0x110
	v_lshrrev_b32_e32 v15, 4, v15
	v_and_b32_e32 v8, -8, v5
	v_mad_u64_u32 v[112:113], s[18:19], v5, s28, v[2:3]
	v_add_u32_e32 v5, 0x200, v212
	v_mad_u64_u32 v[116:117], s[18:19], v15, s28, v[2:3]
	v_add_u32_e32 v15, 0x600, v212
	v_ashrrev_i32_e32 v5, 4, v5
	v_lshrrev_b32_e32 v15, 4, v15
	v_mad_u64_u32 v[114:115], s[18:19], v5, s28, v[2:3]
	v_mad_u64_u32 v[118:119], s[18:19], v15, s28, v[2:3]
	s_movk_i32 s18, 0x88
	v_and_b32_e32 v107, 0x7f, v212
	v_mul_lo_u32 v2, v8, s18
	v_mad_u32_u24 v121, v107, s83, v8
	v_add_u32_e32 v6, 0x88, v107
	v_readlane_b32 s20, v254, 4
	v_add_lshl_u32 v8, v2, v107, 1
	v_readlane_b32 s29, v254, 5
	v_add_lshl_u32 v15, v2, v6, 1
	v_add_u32_e32 v117, s20, v8
	v_add_u32_e32 v113, s29, v8
	v_add_u32_e32 v8, 0x110, v2
	v_add_u32_e32 v115, s29, v15
	v_add_u32_e32 v119, s20, v15
	v_add_lshl_u32 v15, v8, v107, 1
	v_add_lshl_u32 v8, v8, v6, 1
	v_add_u32_e32 v171, s29, v8
	v_add_u32_e32 v173, s20, v8
	v_add_u32_e32 v8, 0x220, v2
	v_add_u32_e32 v170, s29, v15
	v_add_u32_e32 v172, s20, v15
	v_add_lshl_u32 v15, v8, v107, 1
	v_add_lshl_u32 v8, v8, v6, 1
	v_add_u32_e32 v2, 0x330, v2
	v_add_u32_e32 v175, s29, v8
	v_add_u32_e32 v177, s20, v8
	v_add_lshl_u32 v8, v2, v107, 1
	v_add_lshl_u32 v2, v2, v6, 1
	v_add_u32_e32 v179, s29, v2
	v_add_u32_e32 v181, s20, v2
	v_and_b32_e32 v2, 0x1ffffff8, v5
	s_cmp_gt_u32 s38, 63
	v_mul_lo_u32 v2, v2, s18
	v_writelane_b32 v255, s2, 12
	s_cselect_b64 s[2:3], -1, 0
	s_cmp_lt_u32 s38, 64
	v_add_lshl_u32 v5, v2, v107, 1
	v_and_b32_e32 v1, 15, v212
	s_cselect_b64 s[8:9], -1, 0
	v_add_u32_e32 v178, s29, v8
	v_add_u32_e32 v180, s20, v8
	v_add_u32_e32 v182, s29, v5
	v_add_lshl_u32 v8, v2, v6, 1
	v_add_u32_e32 v184, s20, v5
	v_add_u32_e32 v5, 0x110, v2
	v_writelane_b32 v255, s8, 13
	v_lshl_or_b32 v110, s95, 4, v1
	v_lshlrev_b32_e32 v165, 2, v4
	v_add_u32_e32 v183, s29, v8
	v_add_u32_e32 v185, s20, v8
	v_add_lshl_u32 v8, v5, v107, 1
	v_add_lshl_u32 v5, v5, v6, 1
	v_writelane_b32 v255, s9, 14
	v_add_u32_e32 v187, s29, v5
	v_add_u32_e32 v189, s20, v5
	v_add_u32_e32 v5, 0x220, v2
	v_cmp_gt_i32_e64 s[18:19], v165, v110
	v_add_u32_e32 v186, s29, v8
	v_add_u32_e32 v188, s20, v8
	v_add_lshl_u32 v8, v5, v107, 1
	v_add_lshl_u32 v5, v5, v6, 1
	v_add_u32_e32 v2, 0x330, v2
	v_writelane_b32 v255, s18, 15
	v_add_u32_e32 v191, s29, v5
	v_add_u32_e32 v193, s20, v5
	v_add_lshl_u32 v5, v2, v107, 1
	v_add_lshl_u32 v2, v2, v6, 1
	v_writelane_b32 v255, s19, 16
	v_cmp_lt_i32_e64 s[18:19], v165, v110
	v_add_u32_e32 v195, s29, v2
	v_add_u32_e32 v214, s20, v2
	v_writelane_b32 v255, s18, 17
	v_or_b32_e32 v2, 2, v165
	v_and_b32_e32 v10, 48, v212
	v_writelane_b32 v255, s19, 18
	v_cmp_gt_i32_e64 s[18:19], v2, v110
	v_or_b32_e32 v2, 3, v165
	v_add_u32_e32 v167, s20, v10
	v_writelane_b32 v255, s18, 19
	v_add_u32_e32 v176, s20, v15
	v_add_u32_e32 v192, s20, v8
	v_writelane_b32 v255, s19, 20
	v_cmp_gt_i32_e64 s[18:19], v2, v110
	v_or_b32_e32 v2, 16, v165
	v_add_u32_e32 v213, s20, v5
	v_writelane_b32 v255, s18, 21
	s_mov_b32 s36, s95
	v_readlane_b32 s6, v254, 2
	v_writelane_b32 v255, s19, 22
	v_cmp_gt_i32_e64 s[18:19], v2, v110
	v_or_b32_e32 v2, 17, v165
	s_mov_b32 s31, s94
	v_writelane_b32 v255, s18, 23
	v_lshl_add_u32 v153, v211, 3, s6
	s_lshl_b32 s6, s95, 5
	v_writelane_b32 v255, s19, 24
	v_cmp_gt_i32_e64 s[18:19], v2, v110
	v_or_b32_e32 v2, 18, v165
	v_readlane_b32 s8, v254, 3
	v_writelane_b32 v255, s18, 25
	s_add_i32 s7, s8, s6
	s_add_i32 s6, s6, 0
	v_writelane_b32 v255, s19, 26
	v_cmp_gt_i32_e64 s[18:19], v2, v110
	v_or_b32_e32 v2, 19, v165
	s_mov_b64 s[34:35], s[92:93]
	v_writelane_b32 v255, s18, 27
	s_cmp_gt_i32 s95, -1
	v_mov_b32_e32 v12, 0x1100
	v_writelane_b32 v255, s19, 28
	v_cmp_gt_i32_e64 s[18:19], v2, v110
	v_or_b32_e32 v2, 32, v165
	v_cmp_gt_i32_e64 s[20:21], v2, v110
	v_writelane_b32 v255, s18, 29
	v_or_b32_e32 v2, 33, v165
	v_mov_b32_e32 v13, 0x2200
	v_writelane_b32 v255, s19, 30
	v_writelane_b32 v255, s20, 31
	s_cselect_b64 s[94:95], -1, 0
	s_cmp_gt_i32 s36, 0
	v_writelane_b32 v255, s21, 32
	v_cmp_gt_i32_e64 s[20:21], v2, v110
	v_or_b32_e32 v2, 34, v165
	v_cmp_gt_i32_e64 s[40:41], v2, v110
	v_or_b32_e32 v2, 35, v165
	v_cmp_gt_i32_e64 s[42:43], v2, v110
	v_or_b32_e32 v2, 48, v165
	v_cmp_gt_i32_e64 s[44:45], v2, v110
	v_or_b32_e32 v2, 49, v165
	v_cmp_gt_i32_e64 s[46:47], v2, v110
	v_or_b32_e32 v2, 50, v165
	v_writelane_b32 v255, s20, 33
	v_cmp_gt_i32_e64 s[48:49], v2, v110
	v_or_b32_e32 v2, 51, v165
	v_writelane_b32 v255, s21, 34
	v_cmp_gt_i32_e64 s[50:51], v2, v110
	v_or_b32_e32 v2, 64, v165
	v_cmp_gt_i32_e64 s[52:53], v2, v110
	v_or_b32_e32 v2, 0x41, v165
	v_writelane_b32 v255, s36, 35
	v_cmp_gt_i32_e64 s[54:55], v2, v110
	v_or_b32_e32 v2, 0x42, v165
	v_writelane_b32 v255, s31, 36
	v_cmp_gt_i32_e64 s[56:57], v2, v110
	v_or_b32_e32 v2, 0x43, v165
	v_writelane_b32 v255, s31, 37
	v_cmp_gt_i32_e64 s[58:59], v2, v110
	v_or_b32_e32 v2, 0x50, v165
	v_writelane_b32 v255, s34, 38
	s_load_dwordx4 s[84:87], s[34:35], 0x90
	v_cmp_gt_i32_e64 s[60:61], v2, v110
	v_or_b32_e32 v2, 0x70, v211
	v_mad_u32_u24 v12, v1, s28, v12
	v_mad_u32_u24 v13, v1, s28, v13
	v_or_b32_e32 v14, 48, v211
	v_add_u32_e32 v174, s29, v15
	v_add_u32_e32 v190, s29, v8
	v_add_u32_e32 v194, s29, v5
	s_cselect_b64 s[92:93], -1, 0
	s_cmp_gt_i32 s36, 1
	v_mul_u32_u24_e32 v19, 0x110, v2
	v_add_u32_e32 v2, s29, v3
	v_readlane_b32 s29, v254, 6
	s_cselect_b64 s[18:19], -1, 0
	s_cmp_gt_i32 s36, 2
	v_mad_u32_u24 v215, v1, s28, v2
	v_add_u32_e32 v216, v2, v12
	v_add_u32_e32 v217, v2, v13
	v_mad_u32_u24 v218, v14, s28, v2
	v_add_u32_e32 v2, s29, v3
	v_readlane_b32 s29, v254, 7
	s_cselect_b64 s[20:21], -1, 0
	s_cmp_gt_i32 s36, 3
	v_mad_u32_u24 v219, v1, s28, v2
	v_add_u32_e32 v220, v2, v12
	v_add_u32_e32 v221, v2, v13
	v_mad_u32_u24 v222, v14, s28, v2
	v_add_u32_e32 v2, s29, v3
	v_readlane_b32 s29, v254, 8
	v_writelane_b32 v255, s35, 39
	s_cselect_b64 s[22:23], -1, 0
	s_cmp_gt_i32 s36, 4
	v_mad_u32_u24 v223, v1, s28, v2
	v_add_u32_e32 v224, v2, v12
	v_add_u32_e32 v225, v2, v13
	v_mad_u32_u24 v226, v14, s28, v2
	v_add_u32_e32 v2, s29, v3
	s_waitcnt lgkmcnt(0)
; #define LAS __attribute__((address_space(3)))
; #define SSD_SCAN(buf) do { const int l0 = 2 * lane; const float a0 = A * d0, a1 = A * d1; float incl = a0 + a1; \
;             _Pragma("unroll") for (int o = 1; o < 64; o <<= 1) { const float tv = __shfl_up(incl, o); if (lane >= o) incl += tv; } \
;             (buf)[l0 + 1] = incl; (buf)[l0] = incl - a1; (buf)[128 + l0] = d0; (buf)[128 + l0 + 1] = d1; } while (0)
; __device__ __forceinline__ void ssd_phase(const bf16_t* XBC, const float* DT  , const ss_t* SSq, const float* dtb, const bf16_t* Z, const float* a_log, const float* d_skip, bf16_t* YS, LAS unsigned char* lds, int tid, int wid, int lane, int bid, int G) {
;     const int fr = lane & 15, fq = lane >> 4;
;     LAS bf16_t* Ct = (LAS bf16_t*)(lds + SS_CT); LAS bf16_t* Bt = (LAS bf16_t*)(lds + SS_BT); LAS bf16_t* XT = (LAS bf16_t*)(lds + SS_XT); LAS bf16_t* XW = (LAS bf16_t*)(lds + SS_XW);
;     LAS bf16_t* Sin = (LAS bf16_t*)(lds + SS_SIN); LAS float* csbuf = (LAS float*)(lds + SS_CS);
;     for (int w = bid; w < 256; w += G) {
;         const int b = w >> 6, h = w & 63, g = h >> 3;
;         const float A = -expf(a_log[h]), Dh = d_skip[h], dtbh = dtb[h];
;         f32x4 Sacc[4];
; #pragma unroll
;         for (int pt = 0; pt < 4; ++pt) Sacc[pt] = (f32x4){0.f, 0.f, 0.f, 0.f};
;         u32x4 cr[4], br[4], xr2[2]; float d0 = 0.f, d1 = 0.f;
;         const unsigned voffC = (unsigned)(((tid >> 4) * SSD_CONV + 5120 + g * 128 + (tid & 15) * 8) * 2), voffX = (unsigned)(((tid & 127) * SSD_CONV + h * 64 + (tid >> 7) * 8) * 2);
;     ...
;         SSD_GLOADS(0);
;         if (wid == 0) { SSD_DTLOAD(0); SSD_SCAN(csbuf); SSD_DTLOAD(1); }
	v_writelane_b32 v255, s84, 40
	v_add_u32_e32 v157, s7, v3
	v_mul_lo_u32 v9, v110, s28
	s_movk_i32 s30, 0x3000
	s_cselect_b64 s[24:25], -1, 0
	s_cmp_gt_i32 s36, 5
	v_mad_u32_u24 v227, v1, s28, v2
	v_add_u32_e32 v228, v2, v12
	v_add_u32_e32 v229, v2, v13
	v_mad_u32_u24 v230, v14, s28, v2
	v_mov_b64_e32 v[2:3], 0x1ac00040
	v_writelane_b32 v255, s85, 41
	v_lshlrev_b32_e32 v106, 1, v211
	v_add_u32_e32 v9, 0, v9
	v_add_u32_e32 v164, 0, v10
	v_lshl_add_u32 v11, v1, 1, s6
	v_mul_u32_u24_e32 v168, 0x110, v1
	v_or_b32_e32 v5, 0x51, v165
	v_or_b32_e32 v6, 0x52, v165
	v_or_b32_e32 v8, 0x53, v165
	s_cselect_b64 s[26:27], -1, 0
	v_or_b32_e32 v15, 0x60, v165
	v_or_b32_e32 v16, 0x61, v165
	v_or_b32_e32 v17, 0x62, v165
	v_or_b32_e32 v18, 0x63, v165
	s_cmp_gt_i32 s36, 6
	v_or_b32_e32 v20, 0x70, v165
	v_or_b32_e32 v21, 0x71, v165
	v_or_b32_e32 v22, 0x72, v165
	v_or_b32_e32 v23, 0x73, v165
	v_mul_u32_u24_e32 v1, 0x880, v4
	v_ashrrev_i32_e32 v111, 31, v110
	v_mad_i64_i32 v[124:125], s[28:29], v110, s30, v[2:3]
	v_mov_b32_e32 v2, 0x20e30800
	v_writelane_b32 v255, s86, 42
	v_add_u32_e32 v166, s8, v10
	v_cmp_eq_u32_e64 s[6:7], 0, v211
	v_cmp_gt_u32_e64 s[8:9], 2, v211
	v_cmp_gt_u32_e64 s[10:11], 4, v211
	v_cmp_gt_u32_e64 s[12:13], 8, v211
	v_cmp_gt_u32_e64 s[14:15], 16, v211
	v_cmp_gt_u32_e64 s[16:17], 32, v211
	v_mul_u32_u24_e32 v169, 0x110, v14
	v_add_u32_e32 v231, 0x1400, v7
	v_or_b32_e32 v120, 0x80, v106
	v_lshlrev_b32_e32 v122, 9, v211
	v_mov_b32_e32 v123, v0
	v_lshl_or_b32 v126, v211, 4, v2
	v_mov_b32_e32 v127, v0
	v_lshlrev_b64 v[128:129], 13, v[110:111]
	v_add_u32_e32 v111, v9, v10
	v_add_u32_e32 v232, v164, v19
	v_add_u32_e32 v233, v11, v1
	s_mov_b32 s36, s31
	v_cmp_gt_i32_e64 s[62:63], v5, v110
	v_cmp_gt_i32_e64 s[64:65], v6, v110
	v_cmp_gt_i32_e64 s[66:67], v8, v110
	v_cmp_gt_i32_e64 s[68:69], v15, v110
	v_cmp_gt_i32_e64 s[70:71], v16, v110
	v_cmp_gt_i32_e64 s[72:73], v17, v110
	v_cmp_gt_i32_e64 s[74:75], v18, v110
	s_cselect_b64 s[28:29], -1, 0
	v_cmp_gt_i32_e64 s[76:77], v20, v110
	v_cmp_gt_i32_e64 s[78:79], v21, v110
	v_cmp_gt_i32_e64 s[80:81], v22, v110
	v_cmp_gt_i32_e64 s[82:83], v23, v110
	v_writelane_b32 v255, s87, 43
	s_branch .LBB0_94

; #define LAS __attribute__((address_space(3)))
; __device__ __forceinline__ void xpose_item(const float* src, int ld, bf16_t* dst, int K, int k0, LAS float* scr, int lane, const float* gk) {
;     if (src) {
; #pragma unroll 8
;         for (int i = 0; i < 32; ++i) { const int kk = 2 * i + (lane >> 5); scr[kk * 33 + (lane & 31)] = __builtin_nontemporal_load(src + (size_t)(k0 + kk) * ld + (lane & 31)); }
;     } else {
; #pragma unroll 8
;         for (int i = 0; i < 32; ++i) { const int kk = 2 * i + (lane >> 5); scr[kk * 33 + (lane & 31)] = 0.f; }
;     }
;     const int c = lane & 7;
;     f32x4 g0 = (f32x4){1.f, 1.f, 1.f, 1.f}, g1 = g0;
;     if (gk) { g0 = *(const f32x4*)(gk + k0 + 8 * c); g1 = *(const f32x4*)(gk + k0 + 8 * c + 4); }
; __device__ __forceinline__ void ssd_phase(const bf16_t* XBC, const float* DT  , const ss_t* SSq, const float* dtb, const bf16_t* Z, const float* a_log, const float* d_skip, bf16_t* YS, LAS unsigned char* lds, int tid, int wid, int lane, int bid, int G) {
;     ...
;         __syncthreads();
;     }
.LBB0_146:
	v_readlane_b32 s72, v255, 7
	v_readlane_b32 s70, v254, 14
	v_readlane_b32 s75, v255, 10
	v_readlane_b32 s78, v254, 16
	v_readlane_b32 s80, v254, 19
	v_readlane_b32 s92, v255, 38
	v_readlane_b32 s69, v254, 13
	v_readlane_b32 s71, v254, 15
	v_readlane_b32 s73, v255, 8
	v_readlane_b32 s74, v255, 9
	v_readlane_b32 s79, v254, 17
	v_readlane_b32 s75, v254, 18
	v_readlane_b32 s81, v254, 20
	s_movk_i32 s82, 0x2000
	s_movk_i32 s83, 0x1800
	s_mov_b32 s84, 0x16000
	s_movk_i32 s85, 0x3000
	s_mov_b32 s87, 0x1ac03000
	s_mov_b32 s88, 0x1ac06000
	s_mov_b32 s89, 0xfffe0
	s_movk_i32 s90, 0xa1
	s_mov_b32 s91, 0x80000
	v_readlane_b32 s93, v255, 39
	v_readlane_b32 s94, v255, 37
	v_readlane_b32 s95, v255, 35
	v_readlane_b32 s76, v255, 6
	v_readlane_b32 s59, v255, 5
	s_cmpk_lg_i32 s59, 0x100
	s_cbranch_scc1 .Lsgx_done
	s_cmpk_lt_i32 s94, 0x80
	s_cbranch_scc1 .Lsgx_done
	s_waitcnt lgkmcnt(0)
	s_barrier
	s_lshl_b32 s59, s94, 3
	s_add_i32 s59, s59, s95
	s_mul_i32 s64, s95, 0x2100
	v_and_b32_e32 v2, 31, v200
	v_lshrrev_b32_e32 v3, 5, v200
	v_lshlrev_b32_e32 v4, 2, v2
	v_mul_u32_u24_e32 v6, 0x84, v3
	v_add3_u32 v6, v6, v4, s64
	v_and_b32_e32 v7, 7, v200
	v_lshrrev_b32_e32 v8, 3, v200
	v_mul_u32_u24_e32 v9, 0x420, v7
	v_lshl_add_u32 v9, v8, 2, v9
	v_add_u32_e32 v9, s64, v9
	s_cmpk_ge_i32 s59, 0x2c00
	s_cbranch_scc1 .Lxpgx_end
	s_load_dwordx2 s[60:61], s[92:93], 0xb8
	s_load_dwordx2 s[62:63], s[92:93], 0xe8
	s_load_dwordx2 s[64:65], s[92:93], 0x18
	v_mov_b32_e32 v5, 0x5800
	v_mul_u32_u24_e32 v5, v3, v5
	v_add_u32_e32 v5, v5, v4
	v_mov_b32_e32 v10, 0x1000
	v_mul_u32_u24_e32 v10, v8, v10
	v_lshl_add_u32 v12, v7, 4, v10
	v_add_u32_e32 v13, 0x8000, v12
	v_add_u32_e32 v14, 0x10000, v12
	v_add_u32_e32 v15, 0x18000, v12
	s_waitcnt lgkmcnt(0)
	s_add_u32 s62, s62, 0x3900000
	s_addc_u32 s63, s63, 0
	s_add_u32 s64, s64, 0x2000
	s_addc_u32 s65, s65, 0
	v_lshlrev_b32_e32 v16, 5, v7
	v_mov_b32_e32 v17, v0
	v_lshl_add_u64 v[16:17], s[64:65], 0, v[16:17]
	s_mul_hi_u32 s64, s59, 0xba2e8c
	s_mul_i32 s65, s64, 0x160
	s_sub_i32 s65, s59, s65
	s_mul_i32 s68, s64, 0x160000
	s_lshr_b32 s66, s65, 3
	s_lshl_b32 s66, s66, 9
	s_add_i32 s68, s68, s66
	s_and_b32 s66, s65, 3
	s_lshl_b32 s66, s66, 7
	s_add_i32 s68, s68, s66
	s_add_i32 s68, s68, 0x2c00000
	s_bitcmp1_b32 s65, 2
	s_movk_i32 s33, 0xb8
	s_cselect_b32 s33, 0xc0, s33
	s_load_dwordx2 s[66:67], s[92:93], s33
	s_waitcnt lgkmcnt(0)
	s_add_u32 s66, s66, s68
	s_addc_u32 s67, s67, 0
	s_lshl_b32 s64, s64, 8
	s_mov_b32 s65, 0
	v_lshl_add_u64 v[18:19], s[64:65], 0, v[16:17]
	global_load_dwordx4 v[52:55], v[18:19], off
	global_load_dwordx4 v[56:59], v[18:19], off offset:16
	v_mov_b32_e32 v11, v5
	global_load_dword v20, v11, s[66:67] nt
	v_add_u32_e32 v11, 0xb000, v11
	global_load_dword v21, v11, s[66:67] nt
	v_add_u32_e32 v11, 0xb000, v11
	global_load_dword v22, v11, s[66:67] nt
	v_add_u32_e32 v11, 0xb000, v11
	global_load_dword v23, v11, s[66:67] nt
	v_add_u32_e32 v11, 0xb000, v11
	global_load_dword v24, v11, s[66:67] nt
	v_add_u32_e32 v11, 0xb000, v11
	global_load_dword v25, v11, s[66:67] nt
	v_add_u32_e32 v11, 0xb000, v11
	global_load_dword v26, v11, s[66:67] nt
	v_add_u32_e32 v11, 0xb000, v11
	global_load_dword v27, v11, s[66:67] nt
	v_add_u32_e32 v11, 0xb000, v11
	global_load_dword v28, v11, s[66:67] nt
	v_add_u32_e32 v11, 0xb000, v11
	global_load_dword v29, v11, s[66:67] nt
	v_add_u32_e32 v11, 0xb000, v11
	global_load_dword v30, v11, s[66:67] nt
	v_add_u32_e32 v11, 0xb000, v11
	global_load_dword v31, v11, s[66:67] nt
	v_add_u32_e32 v11, 0xb000, v11
	global_load_dword v32, v11, s[66:67] nt
	v_add_u32_e32 v11, 0xb000, v11
	global_load_dword v33, v11, s[66:67] nt
	v_add_u32_e32 v11, 0xb000, v11
	global_load_dword v34, v11, s[66:67] nt
	v_add_u32_e32 v11, 0xb000, v11
	global_load_dword v35, v11, s[66:67] nt
	v_add_u32_e32 v11, 0xb000, v11
	global_load_dword v36, v11, s[66:67] nt
	v_add_u32_e32 v11, 0xb000, v11
	global_load_dword v37, v11, s[66:67] nt
	v_add_u32_e32 v11, 0xb000, v11
	global_load_dword v38, v11, s[66:67] nt
	v_add_u32_e32 v11, 0xb000, v11
	global_load_dword v39, v11, s[66:67] nt
	v_add_u32_e32 v11, 0xb000, v11
	global_load_dword v40, v11, s[66:67] nt
	v_add_u32_e32 v11, 0xb000, v11
	global_load_dword v41, v11, s[66:67] nt
	v_add_u32_e32 v11, 0xb000, v11
	global_load_dword v42, v11, s[66:67] nt
	v_add_u32_e32 v11, 0xb000, v11
	global_load_dword v43, v11, s[66:67] nt
	v_add_u32_e32 v11, 0xb000, v11
	global_load_dword v44, v11, s[66:67] nt
	v_add_u32_e32 v11, 0xb000, v11
	global_load_dword v45, v11, s[66:67] nt
	v_add_u32_e32 v11, 0xb000, v11
	global_load_dword v46, v11, s[66:67] nt
	v_add_u32_e32 v11, 0xb000, v11
	global_load_dword v47, v11, s[66:67] nt
	v_add_u32_e32 v11, 0xb000, v11
	global_load_dword v48, v11, s[66:67] nt
	v_add_u32_e32 v11, 0xb000, v11
	global_load_dword v49, v11, s[66:67] nt
	v_add_u32_e32 v11, 0xb000, v11
	global_load_dword v50, v11, s[66:67] nt
	v_add_u32_e32 v11, 0xb000, v11
	global_load_dword v51, v11, s[66:67] nt

; __device__ __forceinline__ void ssd_phase(const bf16_t* XBC, const float* DT  , const ss_t* SSq, const float* dtb, const bf16_t* Z, const float* a_log, const float* d_skip, bf16_t* YS, LAS unsigned char* lds, int tid, int wid, int lane, int bid, int G) {
;     ...
;         __syncthreads();
;     }
.Lxpgx_end:
	s_sub_i32 s59, s59, 0x2c00
	s_movk_i32 s33, 0x84
.Lsgx_done:
.LBB0_147:
	s_mov_b64 s[2:3], 0

; #define LAS __attribute__((address_space(3)))
; __device__ __forceinline__ int xpose_all(const float* src, const float* src2, int ld, int K, int ndst, int nsrc, int mode, bf16_t* dst, int it, int NGW, LAS float* scr, int lane, const float* gvec = nullptr) {
;     const int nblk = ndst / 32, nitems = (K / 64) * nblk;
;     for (; it < nitems; it += NGW) {
; __global__ void __launch_bounds__(512) mega(Args a_byval) {
;     ...
;             it = xpose_all(a.in[23] + (size_t)lyr * D * DFF, a.in[24] + (size_t)lyr * D * DFF, DFF, 2048, 2 * DFF, 2 * DFF, 1, (bf16_t*)(ws + (lyr ? WS_W_GU : WS_W_GU0)), it, NGW, scr, lane, norm_ffn_g + lyr * D);
;             it = xpose_all(a.in[25] + (size_t)lyr * D * DFF, nullptr, 2048, DFF, 2048, 2048, 0, (bf16_t*)(ws + (lyr ? WS_W_D : WS_W_D0)), it, NGW, scr, lane);
.LBB0_644:
	s_add_i32 s28, s12, 0xfffff000
	s_mov_b64 s[8:9], 0x2200000
	s_mov_b64 s[10:11], 0x80000
	s_mov_b64 s[14:15], 0x1a00000
	s_waitcnt lgkmcnt(0)
	s_mov_b64 s[16:17], 0x6500000
	s_mov_b64 s[18:19], 0x3900000
	s_mov_b64 s[12:13], 0x800
	v_mov_b32_e32 v1, 0x1600
	s_cmpk_gt_u32 s28, 0x2bff
	v_mul_u32_u24_e32 v11, s12, v1
	s_cbranch_scc1 .LBB0_658
	v_readlane_b32 vcc_lo, v255, 5
	s_cmpk_lg_i32 vcc_lo, 0x100
	s_cbranch_scc1 .LBB0_645
	s_addk_i32 s28, 0x2c00
	s_branch .LBB0_658
